# MLA K/V LDS-DMA pieces issued with SGPR base + 32-bit per-lane offsets
# speedup vs baseline: 1.0715x; 1.0091x over previous
.LBB0_476:
	s_waitcnt vmcnt(0)
	v_lshlrev_b32_e32 v28, 16, v8
	v_and_b32_e32 v29, 0xffff0000, v8
	v_mov_b32_e32 v31, v26
	v_mov_b32_e32 v26, v25
	v_lshlrev_b32_e32 v6, 16, v12
	v_and_b32_e32 v7, 0xffff0000, v12
	v_mov_b32_e32 v30, v24
	v_pk_mul_f32 v[24:25], v[26:27], v[28:29]
	v_lshlrev_b32_e32 v8, 16, v9
	v_pk_fma_f32 v[24:25], v[30:31], v[6:7], v[24:25] neg_lo:[0,0,1] neg_hi:[0,0,1]
	v_and_b32_e32 v9, 0xffff0000, v9
	v_cvt_pk_bf16_f32 v90, v24, v25
	v_pk_mul_f32 v[24:25], v[30:31], v[28:29]
	v_mov_b32_e32 v12, v20
	v_pk_fma_f32 v[6:7], v[26:27], v[6:7], v[24:25]
	v_lshlrev_b32_e32 v133, 2, v38
	v_cvt_pk_bf16_f32 v94, v6, v7
	v_lshlrev_b32_e32 v6, 16, v13
	v_and_b32_e32 v7, 0xffff0000, v13
	v_mov_b32_e32 v13, v22
	v_mov_b32_e32 v22, v21
	v_pk_mul_f32 v[20:21], v[22:23], v[8:9]
	v_pk_mul_f32 v[8:9], v[12:13], v[8:9]
	v_pk_fma_f32 v[20:21], v[12:13], v[6:7], v[20:21] neg_lo:[0,0,1] neg_hi:[0,0,1]
	v_pk_fma_f32 v[6:7], v[22:23], v[6:7], v[8:9]
	v_lshlrev_b32_e32 v8, 16, v10
	v_and_b32_e32 v9, 0xffff0000, v10
	v_mov_b32_e32 v12, v16
	v_mov_b32_e32 v13, v18
	v_mov_b32_e32 v18, v17
	v_cvt_pk_bf16_f32 v95, v6, v7
	v_lshlrev_b32_e32 v6, 16, v14
	v_and_b32_e32 v7, 0xffff0000, v14
	v_pk_mul_f32 v[16:17], v[18:19], v[8:9]
	v_pk_mul_f32 v[8:9], v[12:13], v[8:9]
	v_pk_fma_f32 v[16:17], v[12:13], v[6:7], v[16:17] neg_lo:[0,0,1] neg_hi:[0,0,1]
	v_pk_fma_f32 v[6:7], v[18:19], v[6:7], v[8:9]
	v_lshlrev_b32_e32 v8, 16, v11
	v_and_b32_e32 v9, 0xffff0000, v11
	v_mov_b32_e32 v11, v4
	v_mov_b32_e32 v4, v3
	v_cvt_pk_bf16_f32 v96, v6, v7
	v_lshlrev_b32_e32 v6, 16, v15
	v_and_b32_e32 v7, 0xffff0000, v15
	v_mov_b32_e32 v10, v2
	v_pk_mul_f32 v[2:3], v[4:5], v[8:9]
	v_lshrrev_b32_e32 v0, 2, v37
	v_pk_fma_f32 v[2:3], v[10:11], v[6:7], v[2:3] neg_lo:[0,0,1] neg_hi:[0,0,1]
	v_and_or_b32 v0, v0, 3, v133
	v_cvt_pk_bf16_f32 v93, v2, v3
	v_pk_mul_f32 v[2:3], v[10:11], v[8:9]
	v_mul_u32_u24_e32 v144, 0xc0, v0
	v_pk_fma_f32 v[2:3], v[4:5], v[6:7], v[2:3]
	v_and_b32_e32 v0, 16, v37
	v_cvt_pk_bf16_f32 v97, v2, v3
	v_lshlrev_b32_e32 v2, 2, v37
	s_lshr_b32 s13, s30, 6
	v_and_or_b32 v0, v2, 12, v0
	s_add_i32 s30, s30, s31
	v_lshlrev_b32_e32 v145, 1, v0
	v_add_u32_e32 v0, s30, v36
	v_mov_b32_e32 v14, v1
	v_mov_b32_e32 v15, v1
	v_cvt_pk_bf16_f32 v91, v20, v21
	s_waitcnt vmcnt(0)
	v_sub_u32_e32 v146, v0, v133
	v_mov_b32_e32 v0, v1
	v_mov_b32_e32 v2, v1
	v_mov_b32_e32 v3, v1
	v_mov_b32_e32 v4, v1
	v_mov_b32_e32 v5, v1
	v_mov_b32_e32 v6, v1
	v_mov_b32_e32 v7, v1
	v_mov_b32_e32 v8, v1
	v_mov_b32_e32 v9, v1
	v_mov_b32_e32 v10, v1
	v_mov_b32_e32 v11, v1
	v_mov_b32_e32 v12, v1
	v_mov_b32_e32 v13, v1
	v_mov_b64_e32 v[32:33], v[14:15]
	v_cvt_pk_bf16_f32 v92, v16, v17
	v_mov_b64_e32 v[30:31], v[12:13]
	v_mov_b64_e32 v[28:29], v[10:11]
	v_mov_b64_e32 v[26:27], v[8:9]
	v_mov_b64_e32 v[24:25], v[6:7]
	v_mov_b64_e32 v[22:23], v[4:5]
	v_mov_b64_e32 v[20:21], v[2:3]
	v_mov_b64_e32 v[18:19], v[0:1]
	v_mov_b64_e32 v[16:17], v[14:15]
	s_or_b32 s7, s4, 31
	s_or_b32 s14, s13, 3
	v_mul_u32_u24_e32 v143, 0xd0, v36
	s_add_i32 s20, s13, 4
	s_mov_b32 s30, 0
	v_mov_b32_e32 v148, 0xefa18f08
	v_mov_b32_e32 v147, 0
	s_mov_b32 s31, 63
	v_subrev_u32_e32 v66, s26, v66
	v_subrev_u32_e32 v68, s26, v68
	v_subrev_u32_e32 v70, s26, v70
	v_subrev_u32_e32 v72, s26, v72
	s_mov_b32 s42, 0
	v_mov_b64_e32 v[202:203], 0
	v_mov_b64_e32 v[204:205], 0
	v_mov_b64_e32 v[206:207], 0
	v_mov_b64_e32 v[208:209], 0
	v_mov_b64_e32 v[210:211], 0
	v_mov_b64_e32 v[212:213], 0
	v_mov_b64_e32 v[214:215], 0
	v_mov_b64_e32 v[216:217], 0
	v_mov_b64_e32 v[218:219], 0
	v_mov_b64_e32 v[220:221], 0
	v_mov_b64_e32 v[222:223], 0
	v_mov_b64_e32 v[224:225], 0
	v_mov_b64_e32 v[226:227], 0
	v_mov_b64_e32 v[228:229], 0
	v_mov_b64_e32 v[230:231], 0
	v_mov_b64_e32 v[232:233], 0
	v_mov_b64_e32 v[14:15], v[12:13]
	v_mov_b64_e32 v[12:13], v[10:11]
	v_mov_b64_e32 v[10:11], v[8:9]
	v_mov_b64_e32 v[8:9], v[6:7]
	v_mov_b64_e32 v[6:7], v[4:5]
	v_mov_b64_e32 v[4:5], v[2:3]
	v_mov_b64_e32 v[2:3], v[0:1]
	s_waitcnt lgkmcnt(0)
	s_barrier
	s_branch .LBB0_478

.LBB0_478:
	s_sub_i32 s8, s31, 63
	s_cmp_le_u32 s8, s7
	s_cselect_b64 s[40:41], -1, 0
	s_cmp_gt_u32 s8, s7
	s_cselect_b64 s[34:35], -1, 0
	s_and_b32 s8, s30, 1
	s_cmp_eq_u32 s8, 0
	s_cselect_b64 s[38:39], -1, 0
	s_cmp_eq_u32 s8, 1
	s_cselect_b64 s[16:17], -1, 0
	s_and_b64 s[34:35], s[34:35], s[38:39]
	s_andn2_b64 vcc, exec, s[34:35]
	s_cbranch_vccnz .LBB0_485
	s_add_i32 s34, s30, 2
	s_cmp_gt_u32 s34, s14
	s_cbranch_scc1 .LBB0_482
	s_and_b32 s8, s34, 2
	s_mulk_i32 s8, 0x6400
	s_add_i32 s34, s8, 0
	s_add_i32 s8, s34, s5
	s_mov_b32 m0, s8
	s_and_b64 vcc, exec, s[36:37]
	global_load_lds_dwordx4 v66, s[26:27]
	s_add_i32 m0, s8, 0x2000
	v_add_u32_e32 v66, v66, v134
	global_load_lds_dwordx4 v68, s[26:27]
	s_add_i32 m0, s8, 0x4000
	v_add_u32_e32 v68, v68, v136
	global_load_lds_dwordx4 v70, s[26:27]
	v_add_u32_e32 v70, v70, v138
	s_cbranch_vccnz .LBB0_482
	s_add_i32 m0, s34, 0x6000
	global_load_lds_dwordx4 v72, s[26:27]
	v_add_u32_e32 v72, v72, v140
.LBB0_482:
	s_cmp_gt_u32 s30, s13
	s_cbranch_scc1 .LBB0_485
	s_add_i32 s8, s30, -1
	s_and_b32 s8, s8, 3
	s_mulk_i32 s8, 0x6400
	s_add_i32 s34, s8, 0
	s_add_i32 s8, s34, s5
	s_mov_b32 m0, s8
	s_and_b64 vcc, exec, s[36:37]
	global_load_lds_dwordx4 v66, s[26:27]
	s_add_i32 m0, s8, 0x2000
	v_add_u32_e32 v66, v66, v134
	global_load_lds_dwordx4 v68, s[26:27]
	s_add_i32 m0, s8, 0x4000
	v_add_u32_e32 v68, v68, v136
	global_load_lds_dwordx4 v70, s[26:27]
	v_add_u32_e32 v70, v70, v138
	s_cbranch_vccnz .LBB0_485
	s_add_i32 m0, s34, 0x6000
	global_load_lds_dwordx4 v72, s[26:27]
	v_add_u32_e32 v72, v72, v140

.Lmla_slow:
	v_add_f32_e32 v254, v202, v203
	v_add_f32_e32 v255, v204, v205
	v_add_f32_e32 v254, v254, v206
	v_add_f32_e32 v255, v255, v207
	v_add_f32_e32 v254, v254, v208
	v_add_f32_e32 v255, v255, v209
	v_add_f32_e32 v254, v254, v210
	v_add_f32_e32 v255, v255, v211
	v_add_f32_e32 v254, v254, v212
	v_add_f32_e32 v255, v255, v213
	v_add_f32_e32 v254, v254, v214
	v_add_f32_e32 v255, v255, v215
	v_add_f32_e32 v254, v254, v216
	v_add_f32_e32 v255, v255, v217
	v_add_f32_e32 v254, v254, v218
	v_add_f32_e32 v255, v255, v219
	v_add_f32_e32 v254, v254, v220
	v_add_f32_e32 v255, v255, v221
	v_add_f32_e32 v254, v254, v222
	v_add_f32_e32 v255, v255, v223
	v_add_f32_e32 v254, v254, v224
	v_add_f32_e32 v255, v255, v225
	v_add_f32_e32 v254, v254, v226
	v_add_f32_e32 v255, v255, v227
	v_add_f32_e32 v254, v254, v228
	v_add_f32_e32 v255, v255, v229
	v_add_f32_e32 v254, v254, v230
	v_add_f32_e32 v255, v255, v231
	v_add_f32_e32 v254, v254, v232
	v_add_f32_e32 v255, v255, v233
	v_add_f32_e32 v254, v254, v255
	v_add_f32_e32 v147, v147, v254
	v_mov_b64_e32 v[202:203], 0
	v_mov_b64_e32 v[204:205], 0
	v_mov_b64_e32 v[206:207], 0
	v_mov_b64_e32 v[208:209], 0
	v_mov_b64_e32 v[210:211], 0
	v_mov_b64_e32 v[212:213], 0
	v_mov_b64_e32 v[214:215], 0
	v_mov_b64_e32 v[216:217], 0
	v_mov_b64_e32 v[218:219], 0
	v_mov_b64_e32 v[220:221], 0
	v_mov_b64_e32 v[222:223], 0
	v_mov_b64_e32 v[224:225], 0
	v_mov_b64_e32 v[226:227], 0
	v_mov_b64_e32 v[228:229], 0
	v_mov_b64_e32 v[230:231], 0
	v_mov_b64_e32 v[232:233], 0
	s_and_b32 s8, s30, 3
	s_mulk_i32 s8, 0x6400
	s_add_i32 s8, s8, 0
	v_add3_u32 v0, s8, v143, v132
	ds_read_b128 v[34:37], v0
	ds_read_b128 v[150:153], v0 offset:32
	ds_read_b128 v[38:41], v0 offset:6656
	ds_read_b128 v[154:157], v0 offset:6688
	ds_read_b128 v[158:161], v0 offset:64
	ds_read_b128 v[162:165], v0 offset:96
	ds_read_b128 v[166:169], v0 offset:6720
	ds_read_b128 v[170:173], v0 offset:6752
	ds_read_b128 v[174:177], v0 offset:128
	ds_read_b128 v[178:181], v0 offset:160
	ds_read_b128 v[194:197], v0 offset:6784
	ds_read_b128 v[198:201], v0 offset:6816
	v_add3_u32 v0, s8, v144, v145
	ds_read_b64_tr_b16 v[126:127], v0 offset:13312
	ds_read_b64_tr_b16 v[128:129], v0 offset:14848
	ds_read_b64_tr_b16 v[124:125], v0 offset:14912
	ds_read_b64_tr_b16 v[122:123], v0 offset:13376
	ds_read_b64_tr_b16 v[118:119], v0 offset:16384
	ds_read_b64_tr_b16 v[120:121], v0 offset:17920
	ds_read_b64_tr_b16 v[116:117], v0 offset:17984
	ds_read_b64_tr_b16 v[114:115], v0 offset:16448
	ds_read_b64_tr_b16 v[110:111], v0 offset:19456
	ds_read_b64_tr_b16 v[112:113], v0 offset:20992
	ds_read_b64_tr_b16 v[108:109], v0 offset:21056
	ds_read_b64_tr_b16 v[106:107], v0 offset:19520
	ds_read_b64_tr_b16 v[102:103], v0 offset:22528
	ds_read_b64_tr_b16 v[104:105], v0 offset:24064
	ds_read_b64_tr_b16 v[100:101], v0 offset:24128
	ds_read_b64_tr_b16 v[98:99], v0 offset:22592
	s_waitcnt lgkmcnt(0)
	v_mfma_f32_32x32x16_bf16 v[50:65], v[34:37], v[74:77], 0
	v_mfma_f32_32x32x16_bf16 v[34:49], v[38:41], v[74:77], 0
	v_mfma_f32_32x32x16_bf16 v[50:65], v[150:153], v[78:81], v[50:65]
	v_mfma_f32_32x32x16_bf16 v[34:49], v[154:157], v[78:81], v[34:49]
	v_mfma_f32_32x32x16_bf16 v[50:65], v[158:161], v[82:85], v[50:65]
	v_mfma_f32_32x32x16_bf16 v[34:49], v[166:169], v[82:85], v[34:49]
	v_mfma_f32_32x32x16_bf16 v[50:65], v[162:165], v[86:89], v[50:65]
	v_mfma_f32_32x32x16_bf16 v[34:49], v[170:173], v[86:89], v[34:49]
	v_mfma_f32_32x32x16_bf16 v[50:65], v[174:177], v[90:93], v[50:65]
	v_mfma_f32_32x32x16_bf16 v[34:49], v[194:197], v[90:93], v[34:49]
	v_mfma_f32_32x32x16_bf16 v[50:65], v[178:181], v[94:97], v[50:65]
	v_mfma_f32_32x32x16_bf16 v[34:49], v[198:201], v[94:97], v[34:49]
	s_andn2_b64 vcc, exec, s[38:39]
	s_cbranch_vccnz .LBB0_493
	s_add_i32 s34, s30, 2
	s_cmp_gt_u32 s34, s14
	s_cbranch_scc1 .LBB0_490
	s_and_b32 s8, s34, 2
	s_mulk_i32 s8, 0x6400
	s_add_i32 s34, s8, 0
	s_add_i32 s8, s34, s5
	s_mov_b32 m0, s8
	s_and_b64 vcc, exec, s[36:37]
	global_load_lds_dwordx4 v66, s[26:27]
	s_add_i32 m0, s8, 0x2000
	v_add_u32_e32 v66, v66, v134
	global_load_lds_dwordx4 v68, s[26:27]
	s_add_i32 m0, s8, 0x4000
	v_add_u32_e32 v68, v68, v136
	global_load_lds_dwordx4 v70, s[26:27]
	v_add_u32_e32 v70, v70, v138
	s_cbranch_vccnz .LBB0_490
	s_add_i32 m0, s34, 0x6000
	global_load_lds_dwordx4 v72, s[26:27]
	v_add_u32_e32 v72, v72, v140

.Lmla_fast_havek:
	s_mov_b32 s42, 0
	s_andn2_b64 vcc, exec, s[38:39]
	s_cbranch_vccnz .Lmla_fast_nodma
	s_add_i32 s34, s30, 2
	s_cmp_gt_u32 s34, s14
	s_cbranch_scc1 .Lmla_fast_d2
	s_and_b32 s8, s34, 2
	s_mulk_i32 s8, 0x6400
	s_add_i32 s34, s8, 0
	s_add_i32 s8, s34, s5
	s_mov_b32 m0, s8
	s_and_b64 vcc, exec, s[36:37]
	global_load_lds_dwordx4 v66, s[26:27]
	s_add_i32 m0, s8, 0x2000
	v_add_u32_e32 v66, v66, v134
	global_load_lds_dwordx4 v68, s[26:27]
	s_add_i32 m0, s8, 0x4000
	v_add_u32_e32 v68, v68, v136
	global_load_lds_dwordx4 v70, s[26:27]
	v_add_u32_e32 v70, v70, v138
	s_cbranch_vccnz .Lmla_fast_d2
	s_add_i32 m0, s34, 0x6000
	global_load_lds_dwordx4 v72, s[26:27]
	v_add_u32_e32 v72, v72, v140
